# lagging wave group: rescale test branches on vcc directly (v_cmp_nge + s_cbranch_vccnz), s_cmp_eq_u64 and s_cselect dropped from the per-tile path
# speedup vs baseline: 1.0133x; 1.0076x over previous
; __device__ __forceinline__ void partialSM(f32x16& p0, f32x16& p1, float& m_reg, float& mn, float& alpha) {
;   constexpr float C = SCALE * 1.4426950408889634f;
;   float pmax = p0[0];
; #pragma unroll
;   for (int r = 1; r < 16; ++r) pmax = fmaxf(pmax, p0[r]);
; #pragma unroll
;   for (int r = 0; r < 16; ++r) pmax = fmaxf(pmax, p1[r]);
;   { auto rr = __builtin_amdgcn_permlane32_swap(__float_as_uint(pmax), __float_as_uint(pmax), false, false);
;     pmax = fmaxf(__uint_as_float(rr[0]), __uint_as_float(rr[1])); }
;   if (__builtin_expect(__all(pmax - m_reg <= THR / SCALE), 1)) { mn = m_reg; alpha = 1.f; }
;   else { mn = fmaxf(m_reg, pmax); alpha = __builtin_amdgcn_exp2f((m_reg - mn) * C); m_reg = mn; }
.Lback0_b:
	v_max3_f32 v144, v64, v65, v66
	v_max3_f32 v145, v80, v81, v82
	v_max3_f32 v144, v144, v67, v68
	v_max3_f32 v145, v145, v83, v84
	v_max3_f32 v144, v144, v69, v70
	v_max3_f32 v145, v145, v85, v86
	v_max3_f32 v144, v144, v71, v72
	v_max3_f32 v145, v145, v87, v88
	v_max3_f32 v144, v144, v73, v74
	v_max3_f32 v145, v145, v89, v90
	v_max3_f32 v144, v144, v75, v76
	v_max3_f32 v145, v145, v91, v92
	v_max3_f32 v144, v144, v77, v78
	v_max3_f32 v145, v145, v93, v94
	v_max3_f32 v144, v144, v79, v95
	v_max_f32_e32 v144, v144, v145
	v_mov_b32_e32 v145, v144
	s_nop 1
	v_permlane32_swap_b32_e32 v144, v145
	v_max_f32_e32 v144, v144, v145
	v_sub_f32_e32 v145, v144, v220
	v_cmp_nge_f32_e32 vcc, s30, v145
	s_waitcnt lgkmcnt(0)
	s_barrier
	v_mov_b32_e32 v222, v76
	v_mov_b32_e32 v223, v77
	v_mov_b32_e32 v76, v90
	v_mov_b32_e32 v77, v91
	v_mov_b32_e32 v226, v72
	v_mov_b32_e32 v227, v73
	v_mov_b32_e32 v224, v74
	v_mov_b32_e32 v225, v75
	v_mov_b32_e32 v74, v92
	v_mov_b32_e32 v75, v93
	v_mov_b32_e32 v73, v94
	v_mov_b32_e32 v72, v95
	s_cbranch_vccnz .Lslow_b0
	v_mov_b32_e32 v221, 1.0

; #define QSTEP(d, A, B, NA, NB) do { if ((d) + 2 < 12) { NA = KLD((d) + 2, 0); NB = KLD((d) + 2, 1); } SBAR(); \
;     p0 = __builtin_amdgcn_mfma_f32_32x32x16_bf16(A, qr[d], p0, 0, 0, 0); p1 = __builtin_amdgcn_mfma_f32_32x32x16_bf16(B, qr[d], p1, 0, 0, 0); SBAR(); } while (0)
; __device__ __forceinline__ void partialSM(f32x16& p0, f32x16& p1, float& m_reg, float& mn, float& alpha) {
;   constexpr float C = SCALE * 1.4426950408889634f;
;   float pmax = p0[0];
; #pragma unroll
;   for (int r = 1; r < 16; ++r) pmax = fmaxf(pmax, p0[r]);
; #pragma unroll
;   for (int r = 0; r < 16; ++r) pmax = fmaxf(pmax, p1[r]);
;   { auto rr = __builtin_amdgcn_permlane32_swap(__float_as_uint(pmax), __float_as_uint(pmax), false, false);
;     pmax = fmaxf(__uint_as_float(rr[0]), __uint_as_float(rr[1])); }
;   if (__builtin_expect(__all(pmax - m_reg <= THR / SCALE), 1)) { mn = m_reg; alpha = 1.f; }
;   else { mn = fmaxf(m_reg, pmax); alpha = __builtin_amdgcn_exp2f((m_reg - mn) * C); m_reg = mn; }
; __device__ __forceinline__ void qkt2(f32x16& p0, f32x16& p1, const char* Ks, const bf16x8* qr, const int* kb4) {
;     ...
;   QSTEP(0, a0, b0, a2, b2); QSTEP(1, a1, b1, a0, b0); QSTEP(2, a2, b2, a1, b1);
;   QSTEP(3, a0, b0, a2, b2); QSTEP(4, a1, b1, a0, b0); QSTEP(5, a2, b2, a1, b1);
;   QSTEP(6, a0, b0, a2, b2); QSTEP(7, a1, b1, a0, b0); QSTEP(8, a2, b2, a1, b1);
;   QSTEP(9, a0, b0, a2, b2); QSTEP(10, a1, b1, a0, b0); QSTEP(11, a2, b2, a1, b1);
.LBB0_447:
	s_waitcnt lgkmcnt(5)
	v_mfma_f32_32x32x16_bf16 v[80:95], v[194:197], v[112:115], v[80:95]
	v_mfma_f32_32x32x16_bf16 v[64:79], v[224:227], v[112:115], v[64:79]
	ds_read_b128 v[194:197], v207 offset:57472
	ds_read_b128 v[224:227], v219 offset:12416
	s_waitcnt lgkmcnt(4)
	v_mfma_f32_32x32x16_bf16 v[80:95], v[228:231], v[116:119], v[80:95]
	v_mfma_f32_32x32x16_bf16 v[64:79], v[232:235], v[116:119], v[64:79]
	ds_read_b128 v[228:231], v210 offset:57600
	ds_read_b128 v[232:235], v216 offset:12544
	s_waitcnt lgkmcnt(4)
	v_mfma_f32_32x32x16_bf16 v[80:95], v[236:239], v[120:123], v[80:95]
	v_mfma_f32_32x32x16_bf16 v[64:79], v[240:243], v[120:123], v[64:79]
	ds_read_b128 v[236:239], v209 offset:57600
	ds_read_b128 v[240:243], v217 offset:12544
	s_waitcnt lgkmcnt(4)
	v_mfma_f32_32x32x16_bf16 v[80:95], v[194:197], v[124:127], v[80:95]
	v_mfma_f32_32x32x16_bf16 v[64:79], v[224:227], v[124:127], v[64:79]
	ds_read_b128 v[194:197], v208 offset:57600
	ds_read_b128 v[224:227], v218 offset:12544
	s_waitcnt lgkmcnt(4)
	v_mfma_f32_32x32x16_bf16 v[80:95], v[228:231], v[132:135], v[80:95]
	v_mfma_f32_32x32x16_bf16 v[64:79], v[232:235], v[132:135], v[64:79]
	ds_read_b128 v[228:231], v207 offset:57600
	ds_read_b128 v[232:235], v219 offset:12544
	s_waitcnt lgkmcnt(4)
	v_mfma_f32_32x32x16_bf16 v[80:95], v[236:239], v[140:143], v[80:95]
	v_mfma_f32_32x32x16_bf16 v[64:79], v[240:243], v[140:143], v[64:79]
	s_waitcnt lgkmcnt(2)
	v_mfma_f32_32x32x16_bf16 v[80:95], v[194:197], v[128:131], v[80:95]
	v_mfma_f32_32x32x16_bf16 v[64:79], v[224:227], v[128:131], v[64:79]
	s_waitcnt lgkmcnt(0)
	v_mfma_f32_32x32x16_bf16 v[80:95], v[228:231], v[136:139], v[80:95]
	v_mfma_f32_32x32x16_bf16 v[64:79], v[232:235], v[136:139], v[64:79]
	s_nop 9
	v_max_f32_e32 v194, v81, v81
	v_max_f32_e32 v195, v80, v80
	v_max_f32_e32 v194, v195, v194
	v_max3_f32 v194, v194, v82, v83
	v_max3_f32 v194, v194, v84, v85
	v_max3_f32 v194, v194, v86, v87
	v_max3_f32 v194, v194, v88, v89
	v_max3_f32 v194, v194, v90, v91
	v_max3_f32 v194, v194, v92, v93
	v_max3_f32 v194, v194, v94, v95
	v_max3_f32 v194, v194, v64, v65
	v_max3_f32 v194, v194, v66, v67
	v_max3_f32 v194, v194, v68, v69
	v_max3_f32 v194, v194, v70, v71
	v_max3_f32 v194, v194, v72, v73
	v_max3_f32 v194, v194, v74, v75
	v_max3_f32 v194, v194, v76, v77
	v_max3_f32 v194, v194, v78, v79
	v_mov_b32_e32 v195, v194
	s_nop 1
	v_permlane32_swap_b32_e32 v194, v195
	v_max_f32_e32 v195, v195, v195
	v_max_f32_e32 v194, v194, v194
	v_max_f32_e32 v194, v194, v195
	v_sub_f32_e32 v196, v194, v220
	v_cmp_nge_f32_e32 vcc, s30, v196
	s_waitcnt lgkmcnt(0)
	s_barrier
	s_cbranch_vccnz .Lslow_b1
	v_mov_b32_e32 v194, 1.0
